# v25 + third wait of a trickle iteration relaxed to vmcnt(9)
# speedup vs baseline: 1.0100x; 1.0092x over previous
; #define PG8_STAGE(bufoff, gbase, voff) do { _Pragma("unroll") for (int _i = 0; _i < 2; ++_i) \
;         __builtin_amdgcn_global_load_lds((const unsigned*)((const char*)(gbase) + (voff)[_i]), (PG8_LAS unsigned*)(lds + (bufoff) + ldsw + _i * 8192), 16, 0, 0); } while (0)
; #define PG8_LDA(dst, b, h) do { _Pragma("unroll") for (int m = 0; m < 4; ++m) _Pragma("unroll") for (int k = 0; k < 2; ++k) dst[m][k] = *(const PG8_LAS bf16x8*)(lds + PG8_SA(b, h) + aoff + m * 2048 + k * 1024); } while (0)
; #define PG8_LDB(dst, b, h) do { _Pragma("unroll") for (int n = 0; n < 2; ++n) _Pragma("unroll") for (int k = 0; k < 2; ++k) dst[n][k] = *(const PG8_LAS bf16x8*)(lds + PG8_SB(b, h) + boff + n * 2048 + k * 1024); } while (0)
; #define PG8_WAIT_V(n) asm volatile("s_waitcnt vmcnt(" #n ")" ::: "memory")
; #define PG8_WAIT_L(n) asm volatile("s_waitcnt lgkmcnt(" #n ")" ::: "memory")
; #define PG8_BAR __builtin_amdgcn_s_barrier()
; #define PG8_SCHED __builtin_amdgcn_sched_barrier(0)
;     ...
;             PG8_WAIT_V(8); PG8_WAIT_L(0); PG8_BAR; PG8_MMA(0, 0, At, B0); PG8_MMA(0, 1, At, B1); PG8_BAR; PG8_SCHED;
;             PG8_LDA(At, 0, 1); PG8_STAGE(PG8_SB(0, 0), b2, voffB); PG8_STAGE(PG8_SB(0, 1), b2 + hstepB, voffB); PG8_STAGE(PG8_SA(0, 0), a2, voffA);
;             PG8_WAIT_V(8); PG8_WAIT_L(0); PG8_BAR; PG8_MMA(1, 0, At, B0); PG8_MMA(1, 1, At, B1); PG8_BAR; PG8_SCHED;
;             PG8_LDB(B0, 1, 0); PG8_LDB(B1, 1, 1); PG8_SCHED; PG8_LDA(At, 1, 0); PG8_STAGE(PG8_SA(0, 1), a2 + hstep, voffA);
;             PG8_WAIT_V(8); PG8_WAIT_L(0); PG8_BAR; PG8_MMA(0, 0, At, B0); PG8_MMA(0, 1, At, B1); PG8_BAR; PG8_SCHED;
.Lpkb_db:
	s_waitcnt lgkmcnt(0)
	s_barrier
	s_setprio 1
	s_waitcnt lgkmcnt(0)
	v_mfma_f32_16x16x32_f16 v[52:55], v[112:115], v[160:163], v[52:55]
	v_mfma_f32_16x16x32_f16 v[48:51], v[120:123], v[160:163], v[48:51]
	v_mfma_f32_16x16x32_f16 v[36:39], v[112:115], v[168:171], v[36:39]
	v_mfma_f32_16x16x32_f16 v[32:35], v[120:123], v[168:171], v[32:35]
	v_mfma_f32_16x16x32_f16 v[20:23], v[112:115], v[202:205], v[20:23]
	v_mfma_f32_16x16x32_f16 v[16:19], v[120:123], v[202:205], v[16:19]
	v_mfma_f32_16x16x32_f16 v[4:7], v[112:115], v[210:213], v[4:7]
	v_mfma_f32_16x16x32_f16 v[0:3], v[120:123], v[210:213], v[0:3]
	v_mfma_f32_16x16x32_f16 v[52:55], v[116:119], v[164:167], v[52:55]
	v_mfma_f32_16x16x32_f16 v[48:51], v[124:127], v[164:167], v[48:51]
	v_mfma_f32_16x16x32_f16 v[36:39], v[116:119], v[192:195], v[36:39]
	v_mfma_f32_16x16x32_f16 v[32:35], v[124:127], v[192:195], v[32:35]
	v_mfma_f32_16x16x32_f16 v[20:23], v[116:119], v[206:209], v[20:23]
	v_mfma_f32_16x16x32_f16 v[16:19], v[124:127], v[206:209], v[16:19]
	v_mfma_f32_16x16x32_f16 v[4:7], v[116:119], v[214:217], v[4:7]
	v_mfma_f32_16x16x32_f16 v[0:3], v[124:127], v[214:217], v[0:3]
	s_setprio 0
	s_setprio 1
	v_mfma_f32_16x16x32_f16 v[60:63], v[144:147], v[160:163], v[60:63]
	v_mfma_f32_16x16x32_f16 v[56:59], v[152:155], v[160:163], v[56:59]
	v_mfma_f32_16x16x32_f16 v[44:47], v[144:147], v[168:171], v[44:47]
	v_mfma_f32_16x16x32_f16 v[40:43], v[152:155], v[168:171], v[40:43]
	v_mfma_f32_16x16x32_f16 v[28:31], v[144:147], v[202:205], v[28:31]
	v_mfma_f32_16x16x32_f16 v[24:27], v[152:155], v[202:205], v[24:27]
	v_mfma_f32_16x16x32_f16 v[12:15], v[144:147], v[210:213], v[12:15]
	v_mfma_f32_16x16x32_f16 v[8:11], v[152:155], v[210:213], v[8:11]
	v_mfma_f32_16x16x32_f16 v[60:63], v[148:151], v[164:167], v[60:63]
	v_mfma_f32_16x16x32_f16 v[56:59], v[156:159], v[164:167], v[56:59]
	v_mfma_f32_16x16x32_f16 v[44:47], v[148:151], v[192:195], v[44:47]
	v_mfma_f32_16x16x32_f16 v[40:43], v[156:159], v[192:195], v[40:43]
	v_mfma_f32_16x16x32_f16 v[28:31], v[148:151], v[206:209], v[28:31]
	v_mfma_f32_16x16x32_f16 v[24:27], v[156:159], v[206:209], v[24:27]
	v_mfma_f32_16x16x32_f16 v[12:15], v[148:151], v[214:217], v[12:15]
	v_mfma_f32_16x16x32_f16 v[8:11], v[156:159], v[214:217], v[8:11]
	s_setprio 0
	s_barrier
	s_add_i32 s57, 0, 0x18000
	s_add_i32 s58, 0, 0x1c000
	v_add_u32_e32 v124, s57, v197
	v_add_u32_e32 v156, s58, v197
	ds_read_b128 v[112:115], v124
	ds_read_b128 v[116:119], v124 offset:1024
	ds_read_b128 v[120:123], v124 offset:2048
	ds_read_b128 v[124:127], v124 offset:3072
	ds_read_b128 v[144:147], v156
	ds_read_b128 v[148:151], v156 offset:1024
	ds_read_b128 v[152:155], v156 offset:2048
	ds_read_b128 v[156:159], v156 offset:3072
	s_add_u32 s26, s26, 0x40000
	s_addc_u32 s27, s27, 0
	s_mov_b32 m0, s42
	v_lshl_add_u64 v[226:227], s[26:27], 0, v[172:173]
	ds_read_b128 v[160:163], v200 offset:32768
	ds_read_b128 v[164:167], v200 offset:33792
	ds_read_b128 v[168:171], v200 offset:34816
	ds_read_b128 v[192:195], v200 offset:35840
	ds_read_b128 v[202:205], v200 offset:36864
	ds_read_b128 v[206:209], v200 offset:37888
	ds_read_b128 v[210:213], v200 offset:38912
	ds_read_b128 v[214:217], v200 offset:39936
	global_load_lds_dwordx4 v[226:227], off
	v_lshl_add_u64 v[226:227], s[26:27], 0, v[176:177]
	s_mov_b32 m0, s43
	s_nop 0
	global_load_lds_dwordx4 v[226:227], off
	s_cmp_eq_u32 s101, 0
	s_cbranch_scc1 .Lpkb_w8c
	s_waitcnt vmcnt(9)
	s_branch .Lpkb_dc

; #define PG8_STAGE(bufoff, gbase, voff) do { _Pragma("unroll") for (int _i = 0; _i < 2; ++_i) \
;         __builtin_amdgcn_global_load_lds((const unsigned*)((const char*)(gbase) + (voff)[_i]), (PG8_LAS unsigned*)(lds + (bufoff) + ldsw + _i * 8192), 16, 0, 0); } while (0)
; #define PG8_LDA(dst, b, h) do { _Pragma("unroll") for (int m = 0; m < 4; ++m) _Pragma("unroll") for (int k = 0; k < 2; ++k) dst[m][k] = *(const PG8_LAS bf16x8*)(lds + PG8_SA(b, h) + aoff + m * 2048 + k * 1024); } while (0)
; #define PG8_WAIT_V(n) asm volatile("s_waitcnt vmcnt(" #n ")" ::: "memory")
; #define PG8_WAIT_L(n) asm volatile("s_waitcnt lgkmcnt(" #n ")" ::: "memory")
; #define PG8_BAR __builtin_amdgcn_s_barrier()
; #define PG8_SCHED __builtin_amdgcn_sched_barrier(0)
;     ...
;             PG8_WAIT_V(8); PG8_WAIT_L(0); PG8_BAR; PG8_MMA(0, 0, At, B0); PG8_MMA(0, 1, At, B1); PG8_BAR; PG8_SCHED;
;             PG8_LDA(At, 1, 1); PG8_STAGE(PG8_SB(1, 0), b3, voffB); PG8_STAGE(PG8_SB(1, 1), b3 + hstepB, voffB); PG8_STAGE(PG8_SA(1, 0), a3, voffA);
;             PG8_WAIT_V(8); PG8_WAIT_L(0); PG8_BAR; PG8_MMA(1, 0, At, B0); PG8_MMA(1, 1, At, B1); PG8_BAR; PG8_SCHED;
;         }
.Lpkb_dc:
	s_waitcnt lgkmcnt(0)
	s_barrier
	s_setprio 1
	s_waitcnt lgkmcnt(0)
	v_mfma_f32_16x16x32_f16 v[132:135], v[112:115], v[160:163], v[132:135]
	v_mfma_f32_16x16x32_f16 v[128:131], v[120:123], v[160:163], v[128:131]
	v_mfma_f32_16x16x32_f16 v[100:103], v[112:115], v[168:171], v[100:103]
	v_mfma_f32_16x16x32_f16 v[96:99], v[120:123], v[168:171], v[96:99]
	v_mfma_f32_16x16x32_f16 v[84:87], v[112:115], v[202:205], v[84:87]
	v_mfma_f32_16x16x32_f16 v[80:83], v[120:123], v[202:205], v[80:83]
	v_mfma_f32_16x16x32_f16 v[68:71], v[112:115], v[210:213], v[68:71]
	v_mfma_f32_16x16x32_f16 v[64:67], v[120:123], v[210:213], v[64:67]
	v_mfma_f32_16x16x32_f16 v[132:135], v[116:119], v[164:167], v[132:135]
	v_mfma_f32_16x16x32_f16 v[128:131], v[124:127], v[164:167], v[128:131]
	v_mfma_f32_16x16x32_f16 v[100:103], v[116:119], v[192:195], v[100:103]
	v_mfma_f32_16x16x32_f16 v[96:99], v[124:127], v[192:195], v[96:99]
	v_mfma_f32_16x16x32_f16 v[84:87], v[116:119], v[206:209], v[84:87]
	v_mfma_f32_16x16x32_f16 v[80:83], v[124:127], v[206:209], v[80:83]
	v_mfma_f32_16x16x32_f16 v[68:71], v[116:119], v[214:217], v[68:71]
	v_mfma_f32_16x16x32_f16 v[64:67], v[124:127], v[214:217], v[64:67]
	s_setprio 0
	s_setprio 1
	v_mfma_f32_16x16x32_f16 v[140:143], v[144:147], v[160:163], v[140:143]
	v_mfma_f32_16x16x32_f16 v[136:139], v[152:155], v[160:163], v[136:139]
	v_mfma_f32_16x16x32_f16 v[108:111], v[144:147], v[168:171], v[108:111]
	v_mfma_f32_16x16x32_f16 v[104:107], v[152:155], v[168:171], v[104:107]
	v_mfma_f32_16x16x32_f16 v[92:95], v[144:147], v[202:205], v[92:95]
	v_mfma_f32_16x16x32_f16 v[88:91], v[152:155], v[202:205], v[88:91]
	v_mfma_f32_16x16x32_f16 v[76:79], v[144:147], v[210:213], v[76:79]
	v_mfma_f32_16x16x32_f16 v[72:75], v[152:155], v[210:213], v[72:75]
	v_mfma_f32_16x16x32_f16 v[140:143], v[148:151], v[164:167], v[140:143]
	v_mfma_f32_16x16x32_f16 v[136:139], v[156:159], v[164:167], v[136:139]
	v_mfma_f32_16x16x32_f16 v[108:111], v[148:151], v[192:195], v[108:111]
	v_mfma_f32_16x16x32_f16 v[104:107], v[156:159], v[192:195], v[104:107]
	v_mfma_f32_16x16x32_f16 v[92:95], v[148:151], v[206:209], v[92:95]
	v_mfma_f32_16x16x32_f16 v[88:91], v[156:159], v[206:209], v[88:91]
	v_mfma_f32_16x16x32_f16 v[76:79], v[148:151], v[214:217], v[76:79]
	v_mfma_f32_16x16x32_f16 v[72:75], v[156:159], v[214:217], v[72:75]
	s_setprio 0
	s_barrier
	s_add_i32 s26, s57, s28
	v_lshl_add_u64 v[218:219], v[218:219], 0, s[10:11]
	s_mov_b32 m0, s26
	ds_read_b128 v[160:163], v200 offset:49152
	ds_read_b128 v[164:167], v200 offset:50176
	ds_read_b128 v[168:171], v200 offset:51200
	ds_read_b128 v[192:195], v200 offset:52224
	ds_read_b128 v[202:205], v200 offset:53248
	ds_read_b128 v[206:209], v200 offset:54272
	ds_read_b128 v[210:213], v200 offset:55296
	ds_read_b128 v[214:217], v200 offset:56320
	global_load_lds_dwordx4 v[218:219], off
	s_add_i32 m0, s26, 0x2000
	s_add_u32 s22, s22, 0x10080
	v_lshl_add_u64 v[218:219], v[220:221], 0, s[10:11]
	s_addc_u32 s23, s23, 0
	s_add_i32 s26, s58, s28
	global_load_lds_dwordx4 v[218:219], off
	v_lshl_add_u64 v[218:219], s[22:23], 0, v[174:175]
	s_mov_b32 m0, s26
	s_nop 0
	global_load_lds_dwordx4 v[218:219], off
	v_lshl_add_u64 v[218:219], s[22:23], 0, v[178:179]
	s_add_i32 m0, s26, 0x2000
	s_nop 0
	global_load_lds_dwordx4 v[218:219], off
	v_lshl_add_u64 v[218:219], v[222:223], 0, s[10:11]
	s_mov_b32 m0, s48
	s_nop 0
	global_load_lds_dwordx4 v[218:219], off
	v_lshl_add_u64 v[218:219], v[224:225], 0, s[10:11]
	s_mov_b32 m0, s49
	s_nop 0
	global_load_lds_dwordx4 v[218:219], off
	s_waitcnt vmcnt(8)
	s_waitcnt lgkmcnt(0)
	s_barrier
	s_setprio 1
	s_waitcnt lgkmcnt(0)
	v_mfma_f32_16x16x32_f16 v[52:55], v[112:115], v[160:163], v[52:55]
	v_mfma_f32_16x16x32_f16 v[48:51], v[120:123], v[160:163], v[48:51]
	v_mfma_f32_16x16x32_f16 v[36:39], v[112:115], v[168:171], v[36:39]
	v_mfma_f32_16x16x32_f16 v[32:35], v[120:123], v[168:171], v[32:35]
	v_mfma_f32_16x16x32_f16 v[20:23], v[112:115], v[202:205], v[20:23]
	v_mfma_f32_16x16x32_f16 v[16:19], v[120:123], v[202:205], v[16:19]
	v_mfma_f32_16x16x32_f16 v[4:7], v[112:115], v[210:213], v[4:7]
	v_mfma_f32_16x16x32_f16 v[0:3], v[120:123], v[210:213], v[0:3]
	v_mfma_f32_16x16x32_f16 v[52:55], v[116:119], v[164:167], v[52:55]
	v_mfma_f32_16x16x32_f16 v[48:51], v[124:127], v[164:167], v[48:51]
	v_mfma_f32_16x16x32_f16 v[36:39], v[116:119], v[192:195], v[36:39]
	v_mfma_f32_16x16x32_f16 v[32:35], v[124:127], v[192:195], v[32:35]
	v_mfma_f32_16x16x32_f16 v[20:23], v[116:119], v[206:209], v[20:23]
	v_mfma_f32_16x16x32_f16 v[16:19], v[124:127], v[206:209], v[16:19]
	v_mfma_f32_16x16x32_f16 v[4:7], v[116:119], v[214:217], v[4:7]
	v_mfma_f32_16x16x32_f16 v[0:3], v[124:127], v[214:217], v[0:3]
	s_setprio 0
	s_setprio 1
	v_mfma_f32_16x16x32_f16 v[60:63], v[144:147], v[160:163], v[60:63]
	v_mfma_f32_16x16x32_f16 v[56:59], v[152:155], v[160:163], v[56:59]
	v_mfma_f32_16x16x32_f16 v[44:47], v[144:147], v[168:171], v[44:47]
	v_mfma_f32_16x16x32_f16 v[40:43], v[152:155], v[168:171], v[40:43]
	v_mfma_f32_16x16x32_f16 v[28:31], v[144:147], v[202:205], v[28:31]
	v_mfma_f32_16x16x32_f16 v[24:27], v[152:155], v[202:205], v[24:27]
	v_mfma_f32_16x16x32_f16 v[12:15], v[144:147], v[210:213], v[12:15]
	v_mfma_f32_16x16x32_f16 v[8:11], v[152:155], v[210:213], v[8:11]
	v_mfma_f32_16x16x32_f16 v[60:63], v[148:151], v[164:167], v[60:63]
	v_mfma_f32_16x16x32_f16 v[56:59], v[156:159], v[164:167], v[56:59]
	v_mfma_f32_16x16x32_f16 v[44:47], v[148:151], v[192:195], v[44:47]
	v_mfma_f32_16x16x32_f16 v[40:43], v[156:159], v[192:195], v[40:43]
	v_mfma_f32_16x16x32_f16 v[28:31], v[148:151], v[206:209], v[28:31]
	v_mfma_f32_16x16x32_f16 v[24:27], v[156:159], v[206:209], v[24:27]
	v_mfma_f32_16x16x32_f16 v[12:15], v[148:151], v[214:217], v[12:15]
	v_mfma_f32_16x16x32_f16 v[8:11], v[156:159], v[214:217], v[8:11]
	s_setprio 0
	s_barrier
	s_cmp_eq_u32 s101, 0
	s_cbranch_scc1 .Lpkb_t
	s_sub_u32 s101, s101, 1
